# v62 + closed-form StaticOrder::next at the G1/G4 unit seams for the resident 256-workgroup grid (same row panel, column tile + 8) instead of two integer divisions through v_rcp/readfirstlane
# speedup vs baseline: 1.0027x; 1.0027x over previous
;     __host__ __device__ bool next(int i_, Unit& u) const {
;         const int i = i_ + i0; if (i >= i1) return false;
;         const long L = (long)i * G + c; if (L >= nwg) return false;
;         int wgid = (int)L; { const int q = nwg / NXCD, r = nwg % NXCD, xcd = wgid % NXCD, off = wgid / NXCD; wgid = (xcd < r ? xcd * (q + 1) : r * (q + 1) + (xcd - r) * q) + off; }
;         const int nig = WGM * nN, gid = wgid / nig, fm = gid * WGM, gsz = (nM - fm) < WGM ? (nM - fm) : WGM;
;         u.pm = fm + ((wgid % nig) % gsz); u.pn = (wgid % nig) / gsz; return true;
;     }
; template <class Epi, class Sched, bool ALIGN_EPI = false, bool SP2 = false, bool KHOOK = false>
; __device__ __forceinline__ void gemm_phase(PG8_LAS unsigned char* lds, const Gemm g, const Sched& S, const Epi& E, const int tid_in) {
;     ...
;         const bool has_next = S.next(ui + 1, nxt);
.LBB0_259:
	s_add_i32 s41, s41, 1
	s_add_i32 s11, s41, s20
	s_cmp_ge_u32 s11, s36
	s_mov_b64 s[22:23], 0
	s_cbranch_scc1 .LBB0_262
	s_cmpk_lg_u32 s94, 0x100
	s_cbranch_scc1 .Lg1_sched_generic
	s_cmp_ge_u32 s11, 10
	s_cbranch_scc1 .LBB0_262
	s_mov_b32 s16, s12
	s_add_i32 s14, s10, 8
	s_mov_b64 s[22:23], -1
	s_branch .LBB0_262
.Lg1_sched_generic:
	s_mul_i32 s15, s11, s66
	s_mul_hi_u32 s17, s11, s94
	s_add_i32 s17, s17, s15
	s_mul_i32 s11, s11, s94
	s_add_u32 s18, s11, s92
	s_addc_u32 s19, s17, s80
	v_cmp_gt_i64_e32 vcc, s[18:19], v[194:195]
	s_cbranch_vccnz .LBB0_262
	s_ashr_i32 s11, s18, 31
	s_lshr_b32 s11, s11, 29
	s_add_i32 s11, s18, s11
	s_ashr_i32 s14, s11, 3
	s_and_b32 s11, s11, -8
	s_sub_i32 s11, s18, s11
	s_cmp_lt_i32 s11, 0
	s_cselect_b32 s15, s4, 0x140
	s_mul_i32 s11, s11, s15
	s_add_i32 s11, s11, s14
	s_mul_hi_i32 s14, s11, 0x66666667
	s_lshr_b32 s15, s14, 31
	s_ashr_i32 s14, s14, 7
	s_add_i32 s14, s14, s15
	s_lshl_b32 s15, s14, 2
	s_sub_i32 s16, 32, s15
	s_min_i32 s16, s16, 4
	s_abs_i32 s17, s16
	v_cvt_f32_u32_e32 v224, s17
	s_sub_i32 s19, 0, s17
	s_mulk_i32 s14, 0x140
	s_sub_i32 s11, s11, s14
	v_rcp_iflag_f32_e32 v224, v224
	s_abs_i32 s14, s11
	s_xor_b32 s18, s11, s16
	s_ashr_i32 s18, s18, 31
	v_mul_f32_e32 v224, 0x4f7ffffe, v224
	v_cvt_u32_f32_e32 v224, v224
	s_nop 0
	v_readfirstlane_b32 s22, v224
	s_mul_i32 s19, s19, s22
	s_mul_hi_u32 s19, s22, s19
	s_add_i32 s22, s22, s19
	s_mul_hi_u32 s19, s14, s22
	s_mul_i32 s22, s19, s17
	s_sub_i32 s14, s14, s22
	s_add_i32 s23, s19, 1
	s_sub_i32 s22, s14, s17
	s_cmp_ge_u32 s14, s17
	s_cselect_b32 s19, s23, s19
	s_cselect_b32 s14, s22, s14
	s_add_i32 s22, s19, 1
	s_cmp_ge_u32 s14, s17
	s_cselect_b32 s14, s22, s19
	s_xor_b32 s14, s14, s18
	s_sub_i32 s14, s14, s18
	s_mul_i32 s16, s14, s16
	s_sub_i32 s11, s11, s16
	s_add_i32 s16, s15, s11
	s_mov_b64 s[22:23], -1

;     __host__ __device__ bool next(int i_, Unit& u) const {
;         const int i = i_ + i0; if (i >= i1) return false;
;         const long L = (long)i * G + c; if (L >= nwg) return false;
;         int wgid = (int)L; { const int q = nwg / NXCD, r = nwg % NXCD, xcd = wgid % NXCD, off = wgid / NXCD; wgid = (xcd < r ? xcd * (q + 1) : r * (q + 1) + (xcd - r) * q) + off; }
;         const int nig = WGM * nN, gid = wgid / nig, fm = gid * WGM, gsz = (nM - fm) < WGM ? (nM - fm) : WGM;
;         u.pm = fm + ((wgid % nig) % gsz); u.pn = (wgid % nig) / gsz; return true;
;     }
; template <class Epi, class Sched, bool ALIGN_EPI = false, bool SP2 = false, bool KHOOK = false>
; __device__ __forceinline__ void gemm_phase(PG8_LAS unsigned char* lds, const Gemm g, const Sched& S, const Epi& E, const int tid_in) {
;     ...
;         const bool has_next = S.next(ui + 1, nxt);
.LBB0_1059:
	s_add_i32 s42, s42, 1
	s_cmp_eq_u32 s42, 0x7fffffff
	s_mov_b64 s[14:15], 0
	s_cbranch_scc1 .LBB0_1062
	s_cmpk_lg_u32 s94, 0x100
	s_cbranch_scc1 .Lg4_sched_generic
	s_lshl_b32 s11, s42, 8
	s_add_i32 s11, s11, s92
	s_cmpk_gt_u32 s11, 0x57f
	s_cbranch_scc1 .LBB0_1062
	s_mov_b32 s12, s18
	s_add_i32 s10, s19, 8
	s_mov_b64 s[14:15], -1
	s_branch .LBB0_1062
.Lg4_sched_generic:
	s_mul_i32 s11, s42, s66
	s_mul_hi_u32 s13, s42, s94
	s_add_i32 s13, s13, s11
	s_mul_i32 s11, s42, s94
	s_add_u32 s16, s11, s92
	s_addc_u32 s17, s13, s80
	v_mov_b64_e32 v[0:1], 0x57f
	v_cmp_gt_i64_e32 vcc, s[16:17], v[0:1]
	s_cbranch_vccnz .LBB0_1062
	s_ashr_i32 s10, s16, 31
	s_lshr_b32 s10, s10, 29
	s_add_i32 s10, s16, s10
	s_ashr_i32 s11, s10, 3
	s_and_b32 s10, s10, -8
	s_sub_i32 s10, s16, s10
	s_cmp_lt_i32 s10, 0
	s_movk_i32 s12, 0xb1
	s_cselect_b32 s12, s12, 0xb0
	s_mul_i32 s10, s10, s12
	s_add_i32 s10, s10, s11
	s_mul_hi_i32 s11, s10, 0x2e8ba2e9
	s_lshr_b32 s12, s11, 31
	s_ashr_i32 s11, s11, 5
	s_add_i32 s11, s11, s12
	s_lshl_b32 s12, s11, 2
	s_sub_i32 s13, 32, s12
	s_min_i32 s13, s13, 4
	s_abs_i32 s14, s13
	v_cvt_f32_u32_e32 v0, s14
	s_sub_i32 s16, 0, s14
	s_mulk_i32 s11, 0xb0
	s_sub_i32 s11, s10, s11
	v_rcp_iflag_f32_e32 v0, v0
	s_abs_i32 s10, s11
	s_xor_b32 s15, s11, s13
	s_ashr_i32 s15, s15, 31
	v_mul_f32_e32 v0, 0x4f7ffffe, v0
	v_cvt_u32_f32_e32 v0, v0
	s_nop 0
	v_readfirstlane_b32 s17, v0
	s_mul_i32 s16, s16, s17
	s_mul_hi_u32 s16, s17, s16
	s_add_i32 s17, s17, s16
	s_mul_hi_u32 s16, s10, s17
	s_mul_i32 s17, s16, s14
	s_sub_i32 s10, s10, s17
	s_add_i32 s22, s16, 1
	s_sub_i32 s17, s10, s14
	s_cmp_ge_u32 s10, s14
	s_cselect_b32 s16, s22, s16
	s_cselect_b32 s10, s17, s10
	s_add_i32 s17, s16, 1
	s_cmp_ge_u32 s10, s14
	s_cselect_b32 s10, s17, s16
	s_xor_b32 s10, s10, s15
	s_sub_i32 s10, s10, s15
	s_mul_i32 s13, s10, s13
	s_sub_i32 s11, s11, s13
	s_add_i32 s12, s12, s11
	s_mov_b64 s[14:15], -1
